# scan passes: waves 4-7 start the group loop about half a group later (s_sleep stagger) so SIMD partners are out of phase
# speedup vs baseline: 1.0051x; 1.0026x over previous
.LBB0_334:
	s_mul_i32 s6, s13, 0x4200
	s_add_i32 s18, s6, 0
	s_add_i32 s6, s12, -7
	s_and_b64 s[14:15], s[2:3], exec
	v_mbcnt_lo_u32_b32 v66, -1, 0
	s_cselect_b32 s12, s12, s6
	v_mbcnt_hi_u32_b32 v161, -1, v66
	s_add_i32 s6, s12, -1
	v_add_u32_e32 v66, s20, v161
	s_max_i32 s6, s6, s8
	v_mov_b32_e32 v69, 0
	v_lshlrev_b32_e32 v68, 1, v66
	s_min_i32 s6, s6, s9
	s_mov_b32 s7, 0
	v_lshl_add_u64 v[158:159], s[88:89], 0, v[68:69]
	s_mulk_i32 s6, 0x1800
	v_lshl_add_u64 v[70:71], v[158:159], 0, s[6:7]
	s_max_i32 s6, s12, s8
	s_min_i32 s6, s6, s9
	s_mulk_i32 s6, 0x1800
	v_lshl_add_u64 v[72:73], v[158:159], 0, s[6:7]
	s_add_i32 s6, s12, 1
	s_max_i32 s6, s6, s8
	s_min_i32 s6, s6, s9
	s_mulk_i32 s6, 0x1800
	v_lshl_add_u64 v[74:75], v[158:159], 0, s[6:7]
	s_add_i32 s6, s12, 2
	s_max_i32 s6, s6, s8
	s_min_i32 s6, s6, s9
	s_mulk_i32 s6, 0x1800
	v_lshl_add_u64 v[76:77], v[158:159], 0, s[6:7]
	s_add_i32 s6, s12, 3
	s_max_i32 s6, s6, s8
	s_min_i32 s6, s6, s9
	s_mulk_i32 s6, 0x1800
	v_lshl_add_u64 v[78:79], v[158:159], 0, s[6:7]
	s_add_i32 s6, s12, 4
	s_max_i32 s6, s6, s8
	s_min_i32 s6, s6, s9
	s_mulk_i32 s6, 0x1800
	v_lshl_add_u64 v[80:81], v[158:159], 0, s[6:7]
	s_add_i32 s6, s12, 5
	s_max_i32 s6, s6, s8
	s_min_i32 s6, s6, s9
	s_mulk_i32 s6, 0x1800
	v_lshl_add_u64 v[82:83], v[158:159], 0, s[6:7]
	s_add_i32 s6, s12, 6
	s_max_i32 s6, s6, s8
	s_min_i32 s6, s6, s9
	s_mulk_i32 s6, 0x1800
	v_lshl_add_u64 v[84:85], v[158:159], 0, s[6:7]
	s_add_i32 s6, s12, 7
	global_load_ushort v236, v[70:71], off
	global_load_ushort v233, v[72:73], off
	global_load_ushort v235, v[74:75], off
	global_load_ushort v232, v[76:77], off
	global_load_ushort v230, v[78:79], off
	global_load_ushort v229, v[80:81], off
	global_load_ushort v228, v[82:83], off
	global_load_ushort v227, v[84:85], off
	s_max_i32 s6, s6, s8
	s_min_i32 s6, s6, s9
	s_mulk_i32 s6, 0x1800
	s_add_i32 s12, s12, 8
	v_lshl_add_u64 v[70:71], v[158:159], 0, s[6:7]
	s_max_i32 s6, s12, s8
	s_min_i32 s6, s6, s9
	s_mulk_i32 s6, 0x1800
	v_lshl_add_u64 v[72:73], v[158:159], 0, s[6:7]
	global_load_ushort v234, v[70:71], off
	global_load_ushort v231, v[72:73], off
	v_cmp_eq_u32_e32 vcc, 0, v1
	s_add_i32 s6, 0, 0x25d00
	v_lshlrev_b32_e32 v71, 2, v161
	v_cndmask_b32_e64 v6, 0, 1.0, vcc
	v_cmp_eq_u32_e32 vcc, 1, v1
	v_add_u32_e32 v170, s6, v71
	s_add_i32 s6, 0, 0x25e00
	v_cndmask_b32_e64 v7, 0, 1.0, vcc
	v_cmp_eq_u32_e32 vcc, 2, v1
	v_add_u32_e32 v171, s6, v71
	s_and_b64 s[6:7], s[2:3], exec
	v_cndmask_b32_e64 v8, 0, 1.0, vcc
	v_cmp_eq_u32_e32 vcc, 3, v1
	v_lshl_add_u32 v67, s19, 6, v161
	s_cselect_b32 s8, 0, 7
	v_cndmask_b32_e64 v9, 0, 1.0, vcc
	v_cmp_eq_u32_e32 vcc, 4, v1
	s_cselect_b32 s12, 1, 6
	s_cselect_b32 s15, 2, 5
	v_cndmask_b32_e64 v2, 0, 1.0, vcc
	v_cmp_eq_u32_e32 vcc, 5, v1
	s_add_i32 s17, s19, 3
	s_sub_i32 s19, 4, s19
	v_cndmask_b32_e64 v3, 0, 1.0, vcc
	v_cmp_eq_u32_e32 vcc, 6, v1
	v_or_b32_e32 v70, 0x900, v67
	v_add_u32_e32 v72, 0x980, v67
	v_cndmask_b32_e64 v4, 0, 1.0, vcc
	v_cmp_eq_u32_e32 vcc, 7, v1
	v_and_b32_e32 v67, 15, v161
	v_lshrrev_b32_e32 v68, 4, v161
	v_cndmask_b32_e64 v5, 0, 1.0, vcc
	v_cmp_eq_u32_e32 vcc, 8, v1
	s_and_b64 s[6:7], s[2:3], exec
	v_lshlrev_b32_e32 v74, 2, v68
	v_cndmask_b32_e64 v10, 0, 1.0, vcc
	v_cmp_eq_u32_e32 vcc, 9, v1
	v_lshl_add_u32 v75, v67, 4, s18
	s_cselect_b32 s6, 5, 2
	v_cndmask_b32_e64 v11, 0, 1.0, vcc
	v_cmp_eq_u32_e32 vcc, 10, v1
	s_cselect_b32 s22, 6, 1
	s_cselect_b32 s24, 7, 0
	v_cndmask_b32_e64 v12, 0, 1.0, vcc
	v_cmp_eq_u32_e32 vcc, 11, v1
	v_add_u32_e32 v76, v75, v74
	s_mul_i32 s9, s8, 0x600
	v_cndmask_b32_e64 v13, 0, 1.0, vcc
	v_cmp_eq_u32_e32 vcc, 12, v1
	s_mul_i32 s14, s12, 0x600
	s_mul_i32 s16, s15, 0x600
	v_cndmask_b32_e64 v14, 0, 1.0, vcc
	v_cmp_eq_u32_e32 vcc, 13, v1
	s_mul_i32 s20, s17, 0x600
	s_mul_i32 s21, s19, 0x600
	v_cndmask_b32_e64 v15, 0, 1.0, vcc
	v_cmp_eq_u32_e32 vcc, 14, v1
	s_mul_i32 s7, s6, 0x600
	s_mul_i32 s23, s22, 0x600
	v_cndmask_b32_e64 v16, 0, 1.0, vcc
	v_cmp_eq_u32_e32 vcc, 15, v1
	s_mul_i32 s25, s24, 0x600
	v_add_u32_e32 v172, s9, v76
	v_cndmask_b32_e64 v17, 0, 1.0, vcc
	v_cmp_eq_u32_e32 vcc, 16, v1
	v_add_u32_e32 v173, s14, v76
	v_add_u32_e32 v174, s16, v76
	v_cndmask_b32_e64 v18, 0, 1.0, vcc
	v_cmp_eq_u32_e32 vcc, 17, v1
	v_add_u32_e32 v175, s20, v76
	v_add_u32_e32 v176, s21, v76
	v_cndmask_b32_e64 v19, 0, 1.0, vcc
	v_cmp_eq_u32_e32 vcc, 18, v1
	v_add_u32_e32 v177, s7, v76
	v_add_u32_e32 v178, s23, v76
	v_cndmask_b32_e64 v20, 0, 1.0, vcc
	v_cmp_eq_u32_e32 vcc, 19, v1
	v_add_u32_e32 v179, s25, v76
	v_add_u32_e32 v76, s18, v71
	v_cndmask_b32_e64 v21, 0, 1.0, vcc
	v_cmp_eq_u32_e32 vcc, 20, v1
	v_add_u32_e32 v187, s7, v76
	s_add_i32 s7, 0, 0x26400
	v_cndmask_b32_e64 v22, 0, 1.0, vcc
	v_cmp_eq_u32_e32 vcc, 21, v1
	s_mulk_i32 s8, 0x90
	v_add_u32_e32 v191, s7, v71
	v_cndmask_b32_e64 v23, 0, 1.0, vcc
	v_cmp_eq_u32_e32 vcc, 22, v1
	s_add_i32 s7, s18, s8
	v_lshlrev_b32_e32 v77, 1, v161
	v_cndmask_b32_e64 v24, 0, 1.0, vcc
	v_cmp_eq_u32_e32 vcc, 23, v1
	s_mulk_i32 s12, 0x90
	v_add_u32_e32 v192, s7, v77
	v_cndmask_b32_e64 v25, 0, 1.0, vcc
	v_cmp_eq_u32_e32 vcc, 24, v1
	s_add_i32 s7, s18, s12
	s_mulk_i32 s15, 0x90
	v_cndmask_b32_e64 v26, 0, 1.0, vcc
	v_cmp_eq_u32_e32 vcc, 25, v1
	v_add_u32_e32 v194, s7, v77
	s_add_i32 s7, s18, s15
	v_cndmask_b32_e64 v27, 0, 1.0, vcc
	v_cmp_eq_u32_e32 vcc, 26, v1
	s_mulk_i32 s17, 0x90
	v_add_u32_e32 v196, s7, v77
	v_cndmask_b32_e64 v28, 0, 1.0, vcc
	v_cmp_eq_u32_e32 vcc, 27, v1
	s_add_i32 s7, s18, s17
	s_mulk_i32 s19, 0x90
	v_cndmask_b32_e64 v29, 0, 1.0, vcc
	v_cmp_eq_u32_e32 vcc, 28, v1
	v_sub_u32_e32 v78, v76, v77
	v_add_u32_e32 v198, s7, v77
	v_cndmask_b32_e64 v30, 0, 1.0, vcc
	v_cmp_eq_u32_e32 vcc, 29, v1
	s_add_i32 s7, s18, s19
	s_mulk_i32 s6, 0x90
	v_cndmask_b32_e64 v31, 0, 1.0, vcc
	v_cmp_eq_u32_e32 vcc, 30, v1
	s_mulk_i32 s22, 0x90
	v_add_u32_e32 v200, s7, v77
	v_cndmask_b32_e64 v32, 0, 1.0, vcc
	v_cmp_eq_u32_e32 vcc, 31, v1
	s_add_i32 s7, s18, s6
	v_add_u32_e32 v203, s6, v78
	v_cndmask_b32_e64 v33, 0, 1.0, vcc
	v_cmp_eq_u32_e32 vcc, 32, v1
	s_add_i32 s6, s18, s22
	s_mulk_i32 s24, 0x90
	v_cndmask_b32_e64 v34, 0, 1.0, vcc
	v_cmp_eq_u32_e32 vcc, 33, v1
	s_add_i32 s26, 0, 0x26000
	v_add_u32_e32 v204, s6, v77
	v_cndmask_b32_e64 v35, 0, 1.0, vcc
	v_cmp_eq_u32_e32 vcc, 34, v1
	s_add_i32 s6, s18, s24
	v_lshlrev_b32_e32 v73, 2, v67
	v_cndmask_b32_e64 v36, 0, 1.0, vcc
	v_cmp_eq_u32_e32 vcc, 35, v1
	v_add_u32_e32 v180, s26, v71
	s_add_i32 s26, 0, 0x26200
	v_cndmask_b32_e64 v37, 0, 1.0, vcc
	v_cmp_eq_u32_e32 vcc, 36, v1
	v_add_u32_e32 v206, s6, v77
	s_add_i32 s6, 0, 0x26600
	v_cndmask_b32_e64 v38, 0, 1.0, vcc
	v_cmp_eq_u32_e32 vcc, 37, v1
	v_mul_u32_u24_e32 v67, 0x48, v67
	v_add_u32_e32 v181, s26, v71
	v_cndmask_b32_e64 v39, 0, 1.0, vcc
	v_cmp_eq_u32_e32 vcc, 38, v1
	v_add_u32_e32 v182, s9, v76
	v_add_u32_e32 v193, s8, v78
	v_cndmask_b32_e64 v40, 0, 1.0, vcc
	v_cmp_eq_u32_e32 vcc, 39, v1
	v_add_u32_e32 v208, s6, v71
	v_lshlrev_b32_e32 v67, 1, v67
	v_cndmask_b32_e64 v41, 0, 1.0, vcc
	v_cmp_eq_u32_e32 vcc, 40, v1
	v_and_b32_e32 v71, 0x70, v161
	s_add_i32 s8, 0, 0x21000
	v_cndmask_b32_e64 v42, 0, 1.0, vcc
	v_cmp_eq_u32_e32 vcc, 41, v1
	s_add_i32 s9, 0, 0x23400
	v_add3_u32 v210, s8, v71, v67
	v_cndmask_b32_e64 v43, 0, 1.0, vcc
	v_cmp_eq_u32_e32 vcc, 42, v1
	v_add3_u32 v211, s9, v71, v67
	v_cmp_lt_i32_e64 s[8:9], 1, v68
	v_cndmask_b32_e64 v44, 0, 1.0, vcc
	v_cmp_eq_u32_e32 vcc, 43, v1
	v_add3_u32 v209, s18, v67, v71
	v_cndmask_b32_e64 v67, 0, 2, s[8:9]
	v_cndmask_b32_e64 v45, 0, 1.0, vcc
	v_cmp_eq_u32_e32 vcc, 44, v1
	v_or_b32_e32 v68, v67, v73
	v_and_b32_e32 v71, 4, v74
	v_cndmask_b32_e64 v46, 0, 1.0, vcc
	v_cmp_eq_u32_e32 vcc, 45, v1
	v_add_u32_e32 v195, s12, v78
	v_lshlrev_b32_e32 v68, 2, v68
	v_cndmask_b32_e64 v47, 0, 1.0, vcc
	v_cmp_eq_u32_e32 vcc, 46, v1
	s_add_i32 s12, 0, 0x25800
	v_mul_u32_u24_e32 v71, 0x180, v71
	v_cndmask_b32_e64 v48, 0, 1.0, vcc
	v_cmp_eq_u32_e32 vcc, 47, v1
	v_add_u32_e32 v202, s7, v77
	v_add_u32_e32 v212, s12, v68
	v_cndmask_b32_e64 v49, 0, 1.0, vcc
	v_cmp_eq_u32_e32 vcc, 48, v1
	s_add_i32 s12, 0, 0x25900
	v_and_b32_e32 v77, 64, v161
	v_cndmask_b32_e64 v50, 0, 1.0, vcc
	v_cmp_eq_u32_e32 vcc, 49, v1
	v_lshlrev_b32_e32 v71, 2, v71
	v_add_u32_e32 v213, s12, v68
	v_cndmask_b32_e64 v51, 0, 1.0, vcc
	v_cmp_eq_u32_e32 vcc, 50, v1
	s_add_i32 s12, 0, 0x25a00
	v_xor_b32_e32 v74, 32, v161
	v_cndmask_b32_e64 v52, 0, 1.0, vcc
	v_cmp_eq_u32_e32 vcc, 51, v1
	v_add_u32_e32 v77, 64, v77
	v_add3_u32 v217, s18, v68, v71
	v_cndmask_b32_e64 v53, 0, 1.0, vcc
	v_cmp_eq_u32_e32 vcc, 52, v1
	v_add_u32_e32 v71, s18, v71
	v_lshl_or_b32 v67, v67, 6, v73
	v_cndmask_b32_e64 v54, 0, 1.0, vcc
	v_cmp_eq_u32_e32 vcc, 53, v1
	v_add_u32_e32 v214, s12, v68
	s_add_i32 s12, 0, 0x25b00
	v_cndmask_b32_e64 v55, 0, 1.0, vcc
	v_cmp_eq_u32_e32 vcc, 54, v1
	v_add_u32_e32 v218, v71, v67
	v_sub_u32_e32 v67, 0, v161
	v_cndmask_b32_e64 v56, 0, 1.0, vcc
	v_cmp_eq_u32_e32 vcc, 55, v1
	v_add_u32_e32 v215, s12, v68
	v_add_u32_e32 v219, v71, v68
	v_cndmask_b32_e64 v57, 0, 1.0, vcc
	v_cmp_eq_u32_e32 vcc, 56, v1
	v_cndmask_b32_e64 v220, v67, v161, s[2:3]
	v_mul_u32_u24_e32 v67, 0x90, v161
	v_cndmask_b32_e64 v58, 0, 1.0, vcc
	v_cmp_eq_u32_e32 vcc, 57, v1
	v_mov_b32_e32 v68, v69
	s_mov_b32 s13, 0
	v_cndmask_b32_e64 v59, 0, 1.0, vcc
	v_cmp_eq_u32_e32 vcc, 58, v1
	v_add_u32_e32 v183, s14, v76
	v_add_u32_e32 v184, s16, v76
	v_cndmask_b32_e64 v60, 0, 1.0, vcc
	v_cmp_eq_u32_e32 vcc, 59, v1
	v_add_u32_e32 v185, s20, v76
	v_add_u32_e32 v186, s21, v76
	v_cndmask_b32_e64 v61, 0, 1.0, vcc
	v_cmp_eq_u32_e32 vcc, 60, v1
	v_add_u32_e32 v189, s23, v76
	v_add_u32_e32 v190, s25, v76
	v_cndmask_b32_e64 v62, 0, 1.0, vcc
	v_cmp_eq_u32_e32 vcc, 61, v1
	v_add_u32_e32 v197, s15, v78
	v_add_u32_e32 v199, s17, v78
	v_cndmask_b32_e64 v63, 0, 1.0, vcc
	v_cmp_eq_u32_e32 vcc, 62, v1
	v_add_u32_e32 v201, s19, v78
	v_add_u32_e32 v205, s22, v78
	v_cndmask_b32_e64 v64, 0, 1.0, vcc
	v_cmp_eq_u32_e32 vcc, 63, v1
	v_add_u32_e32 v207, s24, v78
	v_cmp_gt_i32_e64 s[6:7], 8, v161
	v_cndmask_b32_e64 v65, 0, 1.0, vcc
	v_cmp_lt_i32_e32 vcc, v74, v77
	v_add_u32_e32 v221, 0x300, v75
	v_add_u32_e32 v222, 0x500, v76
	v_cndmask_b32_e32 v74, v161, v74, vcc
	v_lshlrev_b32_e32 v216, 2, v74
	v_lshlrev_b32_e32 v223, 1, v66
	v_lshlrev_b32_e32 v224, 1, v70
	v_lshlrev_b32_e32 v225, 1, v72
	s_movk_i32 s19, 0x7fff
	v_add_u32_e32 v226, s18, v67
	v_mov_b64_e32 v[66:67], v[68:69]
	v_mov_b64_e32 v[72:73], v[68:69]
	v_mov_b64_e32 v[70:71], v[68:69]
	v_mov_b64_e32 v[76:77], v[68:69]
	v_mov_b64_e32 v[74:75], v[68:69]
	v_mov_b64_e32 v[80:81], v[68:69]
	v_mov_b64_e32 v[78:79], v[68:69]
	v_mov_b64_e32 v[84:85], v[68:69]
	v_mov_b64_e32 v[82:83], v[68:69]
	v_mov_b64_e32 v[88:89], v[68:69]
	v_mov_b64_e32 v[86:87], v[68:69]
	v_mov_b64_e32 v[92:93], v[68:69]
	v_mov_b64_e32 v[90:91], v[68:69]
	v_mov_b64_e32 v[96:97], v[68:69]
	v_mov_b64_e32 v[94:95], v[68:69]
	v_mov_b64_e32 v[100:101], v[68:69]
	v_mov_b64_e32 v[98:99], v[68:69]
	v_mov_b64_e32 v[104:105], v[68:69]
	v_mov_b64_e32 v[102:103], v[68:69]
	v_mov_b64_e32 v[108:109], v[68:69]
	v_mov_b64_e32 v[106:107], v[68:69]
	v_mov_b64_e32 v[112:113], v[68:69]
	v_mov_b64_e32 v[110:111], v[68:69]
	v_mov_b64_e32 v[116:117], v[68:69]
	v_mov_b64_e32 v[114:115], v[68:69]
	v_mov_b64_e32 v[120:121], v[68:69]
	v_mov_b64_e32 v[118:119], v[68:69]
	v_mov_b64_e32 v[124:125], v[68:69]
	v_mov_b64_e32 v[122:123], v[68:69]
	v_mov_b64_e32 v[128:129], v[68:69]
	v_mov_b64_e32 v[126:127], v[68:69]
	s_mov_b32 s20, 0
	v_and_b32_e32 v130, 31, v1
	v_lshrrev_b32_e32 v131, 5, v1
	v_bfe_u32 v132, v130, 2, 1
	v_lshrrev_b32_e32 v133, 3, v130
	v_and_b32_e32 v134, 3, v130
	v_lshl_add_u32 v133, v133, 2, v134
	v_cmp_eq_u32_e32 vcc, v132, v131
	s_nop 1
	s_nop 1
	v_mov_b32_e32 v134, 0xff
	v_cndmask_b32_e32 v133, v134, v133, vcc
	v_cmp_eq_u32_e64 s[100:101], 0, v133
	v_mov_b32_e32 v18, 0
	v_mov_b32_e32 v34, 0
	v_cndmask_b32_e64 v2, 0, 1.0, s[100:101]
	v_cndmask_b32_e64 v50, 0, 1.0, s[100:101]
	v_cmp_eq_u32_e64 s[100:101], 1, v133
	v_mov_b32_e32 v19, 0
	v_mov_b32_e32 v35, 0
	v_cndmask_b32_e64 v3, 0, 1.0, s[100:101]
	v_cndmask_b32_e64 v51, 0, 1.0, s[100:101]
	v_cmp_eq_u32_e64 s[100:101], 2, v133
	v_mov_b32_e32 v20, 0
	v_mov_b32_e32 v36, 0
	v_cndmask_b32_e64 v4, 0, 1.0, s[100:101]
	v_cndmask_b32_e64 v52, 0, 1.0, s[100:101]
	v_cmp_eq_u32_e64 s[100:101], 3, v133
	v_mov_b32_e32 v21, 0
	v_mov_b32_e32 v37, 0
	v_cndmask_b32_e64 v5, 0, 1.0, s[100:101]
	v_cndmask_b32_e64 v53, 0, 1.0, s[100:101]
	v_cmp_eq_u32_e64 s[100:101], 4, v133
	v_mov_b32_e32 v22, 0
	v_mov_b32_e32 v38, 0
	v_cndmask_b32_e64 v6, 0, 1.0, s[100:101]
	v_cndmask_b32_e64 v54, 0, 1.0, s[100:101]
	v_cmp_eq_u32_e64 s[100:101], 5, v133
	v_mov_b32_e32 v23, 0
	v_mov_b32_e32 v39, 0
	v_cndmask_b32_e64 v7, 0, 1.0, s[100:101]
	v_cndmask_b32_e64 v55, 0, 1.0, s[100:101]
	v_cmp_eq_u32_e64 s[100:101], 6, v133
	v_mov_b32_e32 v24, 0
	v_mov_b32_e32 v40, 0
	v_cndmask_b32_e64 v8, 0, 1.0, s[100:101]
	v_cndmask_b32_e64 v56, 0, 1.0, s[100:101]
	v_cmp_eq_u32_e64 s[100:101], 7, v133
	v_mov_b32_e32 v25, 0
	v_mov_b32_e32 v41, 0
	v_cndmask_b32_e64 v9, 0, 1.0, s[100:101]
	v_cndmask_b32_e64 v57, 0, 1.0, s[100:101]
	v_cmp_eq_u32_e64 s[100:101], 8, v133
	v_mov_b32_e32 v26, 0
	v_mov_b32_e32 v42, 0
	v_cndmask_b32_e64 v10, 0, 1.0, s[100:101]
	v_cndmask_b32_e64 v58, 0, 1.0, s[100:101]
	v_cmp_eq_u32_e64 s[100:101], 9, v133
	v_mov_b32_e32 v27, 0
	v_mov_b32_e32 v43, 0
	v_cndmask_b32_e64 v11, 0, 1.0, s[100:101]
	v_cndmask_b32_e64 v59, 0, 1.0, s[100:101]
	v_cmp_eq_u32_e64 s[100:101], 10, v133
	v_mov_b32_e32 v28, 0
	v_mov_b32_e32 v44, 0
	v_cndmask_b32_e64 v12, 0, 1.0, s[100:101]
	v_cndmask_b32_e64 v60, 0, 1.0, s[100:101]
	v_cmp_eq_u32_e64 s[100:101], 11, v133
	v_mov_b32_e32 v29, 0
	v_mov_b32_e32 v45, 0
	v_cndmask_b32_e64 v13, 0, 1.0, s[100:101]
	v_cndmask_b32_e64 v61, 0, 1.0, s[100:101]
	v_cmp_eq_u32_e64 s[100:101], 12, v133
	v_mov_b32_e32 v30, 0
	v_mov_b32_e32 v46, 0
	v_cndmask_b32_e64 v14, 0, 1.0, s[100:101]
	v_cndmask_b32_e64 v62, 0, 1.0, s[100:101]
	v_cmp_eq_u32_e64 s[100:101], 13, v133
	v_mov_b32_e32 v31, 0
	v_mov_b32_e32 v47, 0
	v_cndmask_b32_e64 v15, 0, 1.0, s[100:101]
	v_cndmask_b32_e64 v63, 0, 1.0, s[100:101]
	v_cmp_eq_u32_e64 s[100:101], 14, v133
	v_mov_b32_e32 v32, 0
	v_mov_b32_e32 v48, 0
	v_cndmask_b32_e64 v16, 0, 1.0, s[100:101]
	v_cndmask_b32_e64 v64, 0, 1.0, s[100:101]
	v_cmp_eq_u32_e64 s[100:101], 15, v133
	v_mov_b32_e32 v33, 0
	v_mov_b32_e32 v49, 0
	v_cndmask_b32_e64 v17, 0, 1.0, s[100:101]
	v_cndmask_b32_e64 v65, 0, 1.0, s[100:101]
	v_readfirstlane_b32 s100, v188
	s_nop 0
	s_cmp_lt_u32 s100, 256
	s_cbranch_scc1 .Lstag_a_done
	s_mov_b32 s100, 6
.Lstag_a_loop:
	s_sleep 32
	s_sub_u32 s100, s100, 1
	s_cmp_lg_u32 s100, 0
	s_cbranch_scc1 .Lstag_a_loop
.Lstag_a_done:
.LBB0_335:
	s_lshl_b32 s21, s20, 3
	s_add_i32 s21, s21, s1
	s_cmpk_gt_i32 s21, 0xff
	s_cselect_b64 s[14:15], -1, 0
	s_mov_b64 s[16:17], -1
	s_and_b64 vcc, exec, s[14:15]
	s_cbranch_vccz .LBB0_341
	s_and_b64 vcc, exec, s[4:5]
	s_cbranch_vccnz .LBB0_338
	s_sub_i32 s12, 0x40ff, s21
	s_mov_b64 s[16:17], 0

.LBB0_700:
	s_mulk_i32 s2, 0x4200
	s_add_i32 s30, s2, 0
	s_mul_i32 s0, s3, 0x600
	s_add_u32 s8, s88, s0
	s_addc_u32 s9, s89, 0
	s_mul_i32 s3, s3, 48
	s_add_u32 s16, s88, s3
	s_addc_u32 s17, s89, 0
	s_cmp_lg_u32 s21, 0
	v_mbcnt_lo_u32_b32 v66, -1, 0
	s_cselect_b64 s[14:15], -1, 0
	s_add_i32 s2, 0, 0x25d00
	s_add_i32 s3, 0, 0x25e00
	s_add_i32 s1, s21, 3
	s_sub_i32 s0, 4, s21
	v_mbcnt_hi_u32_b32 v72, -1, v66
	s_cmp_eq_u32 s21, 0
	v_lshlrev_b32_e32 v151, 2, v72
	v_add_u32_e32 v156, s2, v151
	v_add_u32_e32 v157, s3, v151
	s_cselect_b64 s[2:3], -1, 0
	v_and_b32_e32 v67, 15, v72
	v_lshrrev_b32_e32 v69, 4, v72
	s_and_b64 s[4:5], s[2:3], exec
	v_sub_u32_e32 v74, 0, v72
	s_cselect_b32 s4, 0, 7
	v_lshlrev_b32_e32 v75, 2, v69
	v_lshlrev_b32_e32 v159, 4, v67
	s_cselect_b32 s6, 1, 6
	s_cselect_b32 s18, 2, 5
	s_cselect_b32 s23, 5, 2
	s_cselect_b32 s25, 6, 1
	s_cselect_b32 s27, 7, 0
	v_lshl_add_u32 v66, s21, 6, v72
	v_cndmask_b32_e64 v158, v74, v72, s[2:3]
	v_add3_u32 v74, s30, v75, v159
	s_mul_i32 s5, s4, 0x600
	s_mul_i32 s7, s6, 0x600
	s_mul_i32 s19, s18, 0x600
	s_mul_i32 s21, s1, 0x600
	s_mul_i32 s22, s0, 0x600
	s_mul_i32 s24, s23, 0x600
	s_mul_i32 s26, s25, 0x600
	s_mul_i32 s28, s27, 0x600
	v_add_u32_e32 v160, s5, v74
	v_add_u32_e32 v161, s7, v74
	v_add_u32_e32 v162, s19, v74
	v_add_u32_e32 v163, s21, v74
	v_add_u32_e32 v164, s22, v74
	v_add_u32_e32 v165, s24, v74
	v_add_u32_e32 v166, s26, v74
	v_add_u32_e32 v167, s28, v74
	v_add_u32_e32 v76, s30, v151
	v_lshlrev_b32_e32 v74, 1, v72
	v_add_u32_e32 v170, s5, v76
	v_add_u32_e32 v171, s7, v76
	v_add_u32_e32 v172, s19, v76
	v_add_u32_e32 v173, s21, v76
	v_add_u32_e32 v174, s22, v76
	v_add_u32_e32 v175, s24, v76
	v_add_u32_e32 v176, s26, v76
	v_add_u32_e32 v177, s28, v76
	s_add_i32 s5, 0, 0x26400
	s_mulk_i32 s4, 0x90
	v_sub_u32_e32 v76, v76, v74
	s_mulk_i32 s6, 0x90
	v_add_u32_e32 v178, s5, v151
	s_add_i32 s5, s30, s4
	v_add_u32_e32 v180, s4, v76
	s_add_i32 s4, s30, s6
	s_mulk_i32 s18, 0x90
	v_add_u32_e32 v181, s4, v74
	s_add_i32 s4, s30, s18
	s_mulk_i32 s1, 0x90
	s_mulk_i32 s0, 0x90
	s_mulk_i32 s23, 0x90
	v_add_u32_e32 v183, s4, v74
	s_add_i32 s4, s30, s1
	v_add_u32_e32 v186, s1, v76
	s_add_i32 s1, s30, s0
	v_add_u32_e32 v189, s0, v76
	s_add_i32 s0, s30, s23
	s_mulk_i32 s25, 0x90
	v_add_u32_e32 v190, s0, v74
	s_add_i32 s0, s30, s25
	s_mulk_i32 s27, 0x90
	v_add_u32_e32 v192, s0, v74
	s_add_i32 s0, s30, s27
	v_add_u32_e32 v182, s6, v76
	v_add_u32_e32 v184, s18, v76
	v_add_u32_e32 v191, s23, v76
	v_add_u32_e32 v193, s25, v76
	v_add_u32_e32 v194, s0, v74
	v_add_u32_e32 v195, s27, v76
	s_add_i32 s0, 0, 0x26600
	v_mul_u32_u24_e32 v76, 0x48, v67
	v_cmp_lt_i32_e64 s[6:7], 1, v69
	v_lshlrev_b32_e32 v71, 2, v67
	v_add_u32_e32 v187, s1, v74
	v_add_u32_e32 v196, s0, v151
	v_lshlrev_b32_e32 v76, 1, v76
	v_and_b32_e32 v77, 0x70, v72
	s_add_i32 s0, 0, 0x21000
	s_add_i32 s1, 0, 0x23400
	v_cndmask_b32_e64 v69, 0, 2, s[6:7]
	v_add3_u32 v197, s30, v76, v77
	v_add3_u32 v198, s0, v77, v76
	v_add3_u32 v199, s1, v77, v76
	v_or_b32_e32 v76, v69, v71
	v_lshlrev_b32_e32 v76, 2, v76
	s_add_i32 s0, 0, 0x25800
	v_add_u32_e32 v200, s0, v76
	s_add_i32 s0, 0, 0x25900
	v_add_u32_e32 v201, s0, v76
	s_add_i32 s0, 0, 0x25a00
	v_and_b32_e32 v78, 64, v72
	v_add_u32_e32 v202, s0, v76
	s_add_i32 s0, 0, 0x25b00
	v_and_b32_e32 v77, 4, v75
	v_xor_b32_e32 v75, 32, v72
	v_add_u32_e32 v78, 64, v78
	v_add_u32_e32 v203, s0, v76
	s_add_i32 s0, 0, 0x25c00
	v_cmp_lt_i32_e32 vcc, v75, v78
	s_add_i32 s29, 0, 0x26000
	v_add_u32_e32 v204, s0, v76
	v_cndmask_b32_e32 v75, v72, v75, vcc
	v_cmp_gt_i32_e32 vcc, 32, v72
	v_cmp_eq_u32_e64 s[0:1], 0, v67
	v_add_u32_e32 v168, s29, v151
	s_add_i32 s29, 0, 0x26200
	s_and_b64 s[0:1], vcc, s[0:1]
	s_lshl_b32 s18, s20, 2
	s_add_u32 s16, s16, s18
	s_addc_u32 s17, s17, 0
	v_mul_u32_u24_e32 v67, 0x180, v77
	s_add_u32 s16, s16, 0xfcb8000
	v_lshlrev_b32_e32 v67, 2, v67
	s_addc_u32 s17, s17, 0
	v_add3_u32 v206, s30, v76, v67
	v_add_u32_e32 v67, s30, v67
	s_lshl_b32 s18, s12, 1
	v_mov_b32_e32 v73, 0
	v_lshl_or_b32 v69, v69, 6, v71
	v_add_u32_e32 v71, 0x600, v67
	s_add_u32 s8, s8, s18
	v_lshlrev_b32_e32 v205, 2, v75
	v_add_u32_e32 v207, v67, v76
	v_add_u32_e32 v208, v67, v69
	v_add_u32_e32 v210, v71, v76
	v_add_u32_e32 v211, v71, v69
	v_add_u32_e32 v71, 0xc00, v67
	v_add_u32_e32 v67, 0x1200, v67
	s_addc_u32 s9, s9, 0
	v_mov_b32_e32 v75, v73
	v_add_u32_e32 v70, s12, v72
	v_or_b32_e32 v68, 0x900, v66
	v_add_u32_e32 v66, 0x980, v66
	v_add_u32_e32 v179, s5, v74
	v_add_u32_e32 v185, s4, v74
	v_cmp_gt_i32_e64 s[4:5], 8, v72
	v_add_u32_e32 v214, v71, v69
	v_add_u32_e32 v216, v67, v76
	v_add_u32_e32 v217, v67, v69
	v_lshl_add_u64 v[74:75], s[8:9], 0, v[74:75]
	s_mov_b64 s[8:9], 0x9d80000
	v_mul_u32_u24_e32 v67, 0x90, v72
	v_mul_u32_u24_e32 v69, 0x90, v77
	v_lshl_add_u64 v[72:73], s[12:13], 0, v[72:73]
	s_movk_i32 s31, 0x600
	s_mulk_i32 s34, 0xd0
	v_add_u32_e32 v169, s29, v151
	v_add_u32_e32 v209, 0x600, v206
	v_add_u32_e32 v212, 0xc00, v206
	v_add_u32_e32 v213, v71, v76
	v_add_u32_e32 v215, 0x1200, v206
	v_lshl_add_u64 v[146:147], v[74:75], 0, s[8:9]
	s_add_i32 s12, s30, 0x3080
	v_lshlrev_b32_e32 v218, 1, v70
	v_lshlrev_b64 v[148:149], 1, v[72:73]
	v_lshlrev_b32_e32 v219, 1, v68
	v_lshlrev_b32_e32 v220, 1, v66
	s_movk_i32 s35, 0x7fff
	v_add_u32_e32 v221, s30, v67
	v_add_u32_e32 v222, s30, v69
	v_readfirstlane_b32 s100, v188
	s_nop 0
	s_cmp_lt_u32 s100, 256
	s_cbranch_scc1 .Lstag_c_done
	s_mov_b32 s100, 6

.Lstag_c_done:
.LBB0_701:
	s_lshl_b32 s36, s13, 3
	s_add_i32 s36, s36, s34
	s_cmpk_gt_i32 s36, 0xff
	s_cselect_b64 s[18:19], -1, 0
	v_cndmask_b32_e64 v66, 0, 1, s[14:15]
	s_mov_b64 s[20:21], -1
	s_and_b64 vcc, exec, s[18:19]
	v_cmp_ne_u32_e64 s[8:9], 1, v66
	s_cbranch_vccz .LBB0_707
	s_and_b64 vcc, exec, s[8:9]
	s_cbranch_vccnz .LBB0_704
	s_sub_i32 s22, 0x40ff, s36
	s_mov_b64 s[20:21], 0
